# v021 with the new norm latch/prologue blocks moved out of line so all other code keeps v020 placement
# baseline (speedup 1.0000x reference)
.LBB0_317:
	v_readlane_b32 s4, v255, 19
	s_and_b64 s[0:1], exec, s[40:41]
	v_readlane_b32 s5, v255, 20
	s_or_b64 s[30:31], s[0:1], s[30:31]
	v_readlane_b32 s0, v255, 17
	v_lshl_add_u64 v[54:55], v[54:55], 0, s[4:5]
	v_readlane_b32 s4, v255, 21
	v_readlane_b32 s1, v255, 18
	v_readlane_b32 s5, v255, 22
	v_lshl_add_u64 v[36:37], v[36:37], 0, s[0:1]
	v_lshl_add_u64 v[56:57], v[56:57], 0, s[4:5]
	v_lshl_add_u64 v[34:35], v[34:35], 0, s[0:1]
	v_lshl_add_u64 v[58:59], v[58:59], 0, s[0:1]
	s_branch .Lnm_latch

.Lnm_latch:
	v_readfirstlane_b32 s18, v32
	s_add_i32 s19, s18, s24
	s_cmp_lt_i32 s19, 0xc000
	s_cbranch_scc0 .Lnm_tail
	s_and_b64 vcc, exec, s[14:15]
	s_cbranch_vccz .Lnm_w8
	s_and_b64 vcc, exec, s[8:9]
	s_cbranch_vccz .Lnm_w7
	s_waitcnt vmcnt(9)
	s_branch .Lnm_cp

.Lnm_cpY:
	v_mov_b64_e32 v[18:19], v[110:111]
	v_mov_b64_e32 v[16:17], v[108:109]
	v_mov_b64_e32 v[22:23], v[106:107]
	v_mov_b64_e32 v[20:21], v[104:105]
	v_mov_b64_e32 v[28:29], v[96:97]
	v_mov_b64_e32 v[30:31], v[98:99]
	v_mov_b64_e32 v[24:25], v[100:101]
	v_mov_b64_e32 v[26:27], v[102:103]
	s_branch .Lnm_cpd
.Lnm_pro:
	v_lshl_add_u64 v[112:113], s[88:89], 0, v[36:37]
	v_lshl_add_u64 v[114:115], s[88:89], 0, v[58:59]
	v_add_co_u32_e32 v112, vcc, 0x8a80000, v112
	s_nop 0
	v_addc_co_u32_e32 v113, vcc, 0, v113, vcc
	global_load_dwordx4 v[0:3], v[114:115], off
	global_load_dwordx4 v[4:7], v[114:115], off offset:1024
	global_load_dwordx4 v[8:11], v[112:113], off
	global_load_dwordx4 v[12:15], v[112:113], off offset:1024
	s_branch .LBB0_318
	s_nop 0
	s_nop 0
	s_nop 0
	s_nop 0
	s_nop 0
	s_nop 0
	s_nop 0
	s_nop 0
	s_nop 0
	s_nop 0
	s_nop 0
	s_nop 0
	s_nop 0
	s_nop 0
	s_nop 0
	s_nop 0
	s_nop 0
	s_nop 0
	s_nop 0
	s_nop 0
	s_nop 0
	s_nop 0
	s_nop 0
	s_nop 0
	s_nop 0
	s_nop 0
	s_nop 0
	s_nop 0
	s_nop 0
	s_nop 0
	s_nop 0
	s_nop 0
	s_nop 0
	s_nop 0
	s_nop 0
	s_nop 0
	s_nop 0
	s_nop 0
	s_nop 0
	s_nop 0
	s_nop 0
	s_nop 0
	s_nop 0
	s_nop 0
	s_nop 0
	s_nop 0
	s_nop 0
	s_nop 0
	s_nop 0
	s_nop 0
	s_nop 0
	s_nop 0
	s_nop 0
	s_nop 0
	s_nop 0
	s_nop 0
	s_nop 0
	s_nop 0
	s_nop 0
	s_nop 0
	s_nop 0
	s_nop 0
	s_nop 0
	s_nop 0
	s_nop 0
	s_nop 0
	s_nop 0
	s_nop 0
	s_nop 0
	s_nop 0
	s_nop 0
	s_nop 0
	s_nop 0
	s_nop 0
	s_nop 0
	s_nop 0
	s_nop 0
	s_nop 0
	s_nop 0
	s_nop 0
	s_nop 0
	s_nop 0
	s_nop 0
	s_nop 0
	s_nop 0
	s_nop 0
	s_nop 0
	s_nop 0
	s_nop 0
	s_nop 0
	s_nop 0
	s_nop 0
	s_nop 0
	s_nop 0
	s_nop 0
	s_nop 0
	s_nop 0
	s_nop 0
	s_nop 0
	s_nop 0
	s_nop 0
	s_nop 0
	s_nop 0
	s_nop 0
	s_nop 0
	s_nop 0
	s_nop 0
	s_nop 0
	s_nop 0
	s_nop 0
	s_nop 0
	s_nop 0
	s_nop 0
	s_nop 0
	s_nop 0
	s_nop 0
	s_nop 0
	s_nop 0
	s_nop 0
	s_nop 0
	s_nop 0
	s_nop 0
	s_nop 0
	s_nop 0
	s_nop 0
	s_nop 0
	s_nop 0
	s_nop 0
	s_nop 0
	s_nop 0
	s_nop 0
	s_nop 0
	s_nop 0
	s_nop 0
	s_nop 0
	s_nop 0
	s_nop 0
	s_nop 0
	s_nop 0
	s_nop 0
	s_nop 0
	s_nop 0
	s_nop 0
	s_nop 0
	s_nop 0
	s_nop 0
	s_nop 0
	s_nop 0
	s_nop 0
	s_nop 0
	s_nop 0
	s_nop 0
	s_nop 0
	s_nop 0
	s_nop 0
	s_nop 0
	s_nop 0
	s_nop 0
	s_nop 0
	s_nop 0
	s_nop 0
	s_nop 0
	s_nop 0
	s_nop 0
	s_nop 0
	s_nop 0
	s_nop 0
	s_nop 0
	s_nop 0
	s_nop 0
	s_nop 0
	s_nop 0
	s_nop 0
	s_nop 0
	s_nop 0
	s_nop 0
	s_nop 0
	s_nop 0
	s_nop 0
	s_nop 0
	s_nop 0
	s_nop 0
	s_nop 0
	s_nop 0
	s_nop 0
	s_nop 0
	s_nop 0
	s_nop 0
	s_nop 0
	s_nop 0
	s_nop 0
	s_nop 0
	s_nop 0
	s_nop 0
	s_nop 0
	s_nop 0
	s_nop 0
	s_nop 0
	s_nop 0
	s_nop 0
	s_nop 0
	s_nop 0
	s_nop 0
	s_nop 0
	s_nop 0
	s_nop 0
	s_nop 0
	s_nop 0
	s_nop 0
	s_nop 0
	s_nop 0
	s_nop 0
	s_nop 0
	s_nop 0
	s_nop 0
	s_nop 0
	s_nop 0
	s_nop 0
	s_nop 0
	s_nop 0
	s_nop 0
	s_nop 0
	s_nop 0
	s_nop 0
	s_nop 0
	s_nop 0
	s_nop 0
	s_nop 0
	s_nop 0
	s_nop 0
	s_nop 0
	s_nop 0
	s_nop 0
	s_nop 0
	s_nop 0
	s_nop 0
	s_nop 0
	s_nop 0
	s_nop 0
	s_nop 0
	s_nop 0
	s_nop 0
	s_nop 0
	s_nop 0
	s_nop 0
	s_nop 0
	s_nop 0
	s_nop 0
	s_nop 0
	s_nop 0
	s_nop 0
	s_nop 0
	s_nop 0
	s_nop 0
	s_nop 0
	s_nop 0
	s_nop 0
	s_nop 0
	s_nop 0
	s_nop 0
	s_nop 0
	s_nop 0
	s_nop 0
	s_nop 0
	s_nop 0
	s_nop 0
	s_nop 0
	s_nop 0
	s_nop 0
	s_nop 0
	s_nop 0
	s_nop 0
	s_nop 0
	s_nop 0
	s_nop 0
	s_nop 0
	s_nop 0
	s_nop 0
	s_nop 0
	s_nop 0
	s_nop 0
	s_nop 0
	s_nop 0
	s_nop 0
	s_nop 0
	s_nop 0
	s_nop 0
	s_nop 0
	s_nop 0
	s_nop 0
	s_nop 0
	s_nop 0
	s_nop 0
	s_nop 0
	s_nop 0
	s_nop 0
	s_nop 0
	s_nop 0
	s_nop 0
	s_nop 0
	s_nop 0
	s_nop 0
	s_nop 0
	s_nop 0
	s_nop 0
	s_nop 0
	s_nop 0
	s_nop 0
	s_nop 0
	s_nop 0
	s_nop 0
	s_nop 0
	s_nop 0
	s_nop 0
	s_nop 0
	s_nop 0
	s_nop 0
	s_nop 0
	s_nop 0
	s_nop 0
	s_nop 0
	s_nop 0
	s_nop 0
	s_nop 0
	s_nop 0
	s_nop 0
	s_nop 0
	s_nop 0
	s_nop 0
	s_nop 0
	s_nop 0
	s_nop 0
	s_nop 0
	s_nop 0
	s_nop 0
	s_nop 0
	s_nop 0
	s_nop 0
	s_nop 0
	s_nop 0
	s_nop 0
	s_nop 0
	s_nop 0
	s_nop 0
	s_nop 0
	s_nop 0
	s_nop 0
	s_nop 0
	s_nop 0
	s_nop 0
	s_nop 0
	s_nop 0
	s_nop 0
	s_nop 0
	s_nop 0
	s_nop 0
	s_nop 0
	s_nop 0
	s_nop 0
	s_nop 0
	s_nop 0
	s_nop 0
	s_nop 0
	s_nop 0
	s_nop 0
	s_nop 0
	s_nop 0
	s_nop 0
	s_nop 0
	s_nop 0
	s_nop 0
	s_nop 0
	s_nop 0
	s_nop 0
	s_nop 0
	s_nop 0
	s_nop 0
	s_nop 0
	s_nop 0
	s_nop 0
	s_nop 0
	s_nop 0
	s_nop 0
	s_nop 0
	s_nop 0
	s_nop 0
	s_nop 0
	s_nop 0
	s_nop 0
	s_nop 0
	s_nop 0
	s_nop 0
	s_nop 0
	s_nop 0
	s_nop 0
	s_nop 0
	s_nop 0
	s_nop 0
	s_nop 0
	s_nop 0
	s_nop 0
	s_nop 0
	s_nop 0
	s_nop 0
	s_nop 0
	s_nop 0
	s_nop 0
	s_nop 0
	s_nop 0
	s_nop 0
	s_nop 0
	s_nop 0
	s_nop 0
	s_nop 0
	s_nop 0
	s_nop 0
	s_nop 0
	s_nop 0
	s_nop 0
	s_nop 0
	s_nop 0
	s_nop 0
	s_nop 0
	s_nop 0
	s_nop 0
	s_nop 0
	s_nop 0
	s_nop 0
	s_nop 0
	s_nop 0
	s_nop 0
	s_nop 0
	s_nop 0
	s_nop 0
	s_nop 0
	s_nop 0
	s_nop 0
	s_nop 0
	s_nop 0
	s_nop 0
	s_nop 0
	s_nop 0
	s_nop 0
	s_nop 0
	s_nop 0
	s_nop 0
	s_nop 0
	s_nop 0
	s_nop 0
	s_nop 0
	s_nop 0
	s_nop 0
	s_nop 0
	s_nop 0
	s_nop 0
	s_nop 0
	s_nop 0
	s_nop 0
	s_nop 0
	s_nop 0
	s_nop 0
	s_nop 0
	s_nop 0
	s_nop 0
	s_nop 0
	s_nop 0
	s_nop 0
	s_nop 0
	s_nop 0
	s_nop 0
	s_nop 0
	s_nop 0
	s_nop 0
	s_nop 0
	s_nop 0
	s_nop 0
	s_nop 0
	s_nop 0
	s_nop 0
	s_nop 0
	s_nop 0
	s_nop 0
	s_nop 0
	s_nop 0
	s_nop 0
	s_nop 0
	s_nop 0
	s_nop 0
	s_nop 0
	s_nop 0
	s_nop 0
	s_nop 0
	s_nop 0
	s_nop 0
	s_nop 0
	s_nop 0
	s_nop 0
	s_nop 0
	s_nop 0
	s_nop 0
	s_nop 0
	s_nop 0
	s_nop 0
	s_nop 0
	s_nop 0
	s_nop 0
	s_nop 0
	s_nop 0
	s_nop 0
	s_nop 0
	s_nop 0
	s_nop 0
	s_nop 0
	s_nop 0
	s_nop 0
	s_nop 0
	s_nop 0
	s_nop 0
	s_nop 0
	s_nop 0
	s_nop 0
	s_nop 0
	s_nop 0
	s_nop 0
	s_nop 0
	s_nop 0
	s_nop 0
	s_nop 0
	s_nop 0
	s_nop 0
	s_nop 0
	s_nop 0
	s_nop 0
	s_nop 0
	s_nop 0
	s_nop 0
	s_nop 0
	s_nop 0
	s_nop 0
	s_nop 0
	s_nop 0
	s_nop 0
	s_nop 0
	s_nop 0
	s_nop 0
	s_nop 0
	s_nop 0
	s_nop 0
	s_nop 0
	s_nop 0
	s_nop 0
	s_nop 0
	s_nop 0
	s_nop 0
	s_nop 0
	s_nop 0
	s_nop 0
	s_nop 0
	s_nop 0
	s_nop 0
	s_nop 0
	s_nop 0
	s_nop 0
	s_nop 0
	s_nop 0
	s_nop 0
	s_nop 0
	s_nop 0
	s_nop 0
	s_nop 0
	s_nop 0
	s_nop 0
	s_nop 0
	s_nop 0
	s_nop 0
	s_nop 0
	s_nop 0
	s_nop 0
	s_nop 0
	s_nop 0
	s_nop 0
	s_nop 0
	s_nop 0
	s_nop 0
	s_nop 0
	s_nop 0
	s_nop 0
	s_nop 0
	s_nop 0
	s_nop 0
	s_nop 0
	s_nop 0
	s_nop 0
	s_nop 0
	s_nop 0
	s_nop 0
	s_nop 0
	s_nop 0
	s_nop 0
	s_nop 0
	s_nop 0
	s_nop 0
	s_nop 0
	s_nop 0
	s_nop 0
	s_nop 0
	s_nop 0
	s_nop 0
	s_nop 0
	s_nop 0
	s_nop 0
	s_nop 0
	s_nop 0
	s_nop 0
	s_nop 0
	s_nop 0
	s_nop 0
	s_nop 0
	s_nop 0
	s_nop 0
	s_nop 0
	s_nop 0
	s_nop 0
	s_nop 0
	s_nop 0
